# fix: pre-loop LDS reads of phase 11 issued in the same first-use order the staged waits of token 0 assume
# speedup vs baseline: 1.0081x; 1.0075x over previous
.Lret2_item:
	s_lshr_b32 s0, s23, 5
	s_and_b32 s1, s23, 31
	s_lshr_b32 s2, s0, 2
	s_and_b32 s3, s0, 3
	s_lshl_b32 s4, s1, 4
	v_lshl_add_u32 v46, v5, 2, s4
	s_and_b32 s4, s1, 3
	s_lshl_b32 s4, s4, 5
	s_add_u32 s4, s4, 128
	v_lshl_add_u32 v3, v5, 3, s4
	s_lshl_b32 s4, s3, 8
	s_add_u32 s4, s4, 1024
	v_lshl_add_u32 v32, v198, 2, s4
	s_add_u32 s4, s4, 4096
	v_lshl_add_u32 v33, v198, 2, s4
	s_lshl_b32 s4, s3, 9
	s_and_b32 s5, s1, 28
	s_lshl_b32 s5, s5, 4
	s_add_u32 s4, s4, s5
	s_add_u32 s4, s4, 2048
	v_min_u32_e32 v42, 31, v198
	v_lshl_add_u32 v34, v42, 2, s4
	v_cmp_lt_u32_e32 vcc, 15, v198
	v_add_u32_e32 v44, 4032, v34
	s_nop 1
	v_cndmask_b32_e32 v34, v34, v44, vcc
	v_readlane_b32 s5, v255, 15
	s_mul_i32 s4, s2, 0x1800000
	s_mul_i32 s1, s5, 0x3000
	s_add_u32 s4, s4, s1
	s_add_u32 s4, s4, 0x3bc0400
	s_add_u32 s10, s8, s4
	s_addc_u32 s11, s9, 0
	s_lshl_b32 s4, s2, 22
	s_lshl_b32 s1, s5, 11
	s_add_u32 s4, s4, s1
	s_lshl_b32 s1, s3, 9
	s_add_u32 s4, s4, s1
	s_add_u32 s4, s4, 0xfd40400
	s_add_u32 s12, s8, s4
	s_addc_u32 s13, s9, 0
	s_lshl_b32 s4, s2, 23
	s_add_u32 s4, s4, s1
	s_add_u32 s4, s4, 333188096
	s_add_u32 s14, s8, s4
	s_addc_u32 s15, s9, 0
	s_lshr_b32 s4, 0x80000, s3
	s_sub_u32 s4, 0x3f800000, s4
	v_mov_b32_e32 v43, s4
	v_rcp_f32_e32 v42, v43
	v_mov_b32_e32 v40, 1.0
	v_mov_b32_e32 v41, 1.0
	s_movk_i32 s20, 256
	s_movk_i32 s21, 24832
	s_mov_b32 s22, 49408
	v_add_u32_e32 v26, s20, v29
	v_add_u32_e32 v27, s20, v30
	v_add_u32_e32 v28, s20, v31
	global_load_dword v84, v32, s[10:11]
	global_load_dword v85, v32, s[10:11] offset:-1024
	global_load_dword v86, v33, s[10:11]
	global_load_dword v87, v33, s[10:11] offset:-1024
	global_load_dword v88, v34, s[10:11]
	global_load_dword v90, v35, s[12:13]
	global_load_dword v91, v35, s[12:13] offset:4
	s_add_u32 s10, s10, 0x18000
	s_addc_u32 s11, s11, 0
	s_add_u32 s12, s12, 0x4000
	s_addc_u32 s13, s13, 0
	s_waitcnt vmcnt(0)
	v_lshlrev_b32_e32 v108, 16, v84
	v_lshlrev_b32_e32 v109, 16, v85
	v_and_b32_e32 v110, s17, v84
	v_and_b32_e32 v111, s17, v85
	v_lshlrev_b32_e32 v112, 16, v86
	v_lshlrev_b32_e32 v113, 16, v87
	v_and_b32_e32 v114, s17, v86
	v_and_b32_e32 v115, s17, v87
	v_lshlrev_b32_e32 v116, 16, v88
	v_and_b32_e32 v117, s17, v88
	ds_write_b128 v29, v[108:111] offset:256
	ds_write_b128 v29, v[112:115] offset:8448
	ds_write_b64 v30, v[90:91] offset:256
	ds_write_b64 v31, v[116:117] offset:256
	v_add_u32_e32 v26, s21, v29
	v_add_u32_e32 v27, s21, v30
	v_add_u32_e32 v28, s21, v31
	global_load_dword v84, v32, s[10:11]
	global_load_dword v85, v32, s[10:11] offset:-1024
	global_load_dword v86, v33, s[10:11]
	global_load_dword v87, v33, s[10:11] offset:-1024
	global_load_dword v88, v34, s[10:11]
	global_load_dword v90, v35, s[12:13]
	global_load_dword v91, v35, s[12:13] offset:4
	s_add_u32 s10, s10, 0x18000
	s_addc_u32 s11, s11, 0
	s_add_u32 s12, s12, 0x4000
	s_addc_u32 s13, s13, 0
	s_waitcnt vmcnt(0)
	v_lshlrev_b32_e32 v108, 16, v84
	v_lshlrev_b32_e32 v109, 16, v85
	v_and_b32_e32 v110, s17, v84
	v_and_b32_e32 v111, s17, v85
	v_lshlrev_b32_e32 v112, 16, v86
	v_lshlrev_b32_e32 v113, 16, v87
	v_and_b32_e32 v114, s17, v86
	v_and_b32_e32 v115, s17, v87
	v_lshlrev_b32_e32 v116, 16, v88
	v_and_b32_e32 v117, s17, v88
	ds_write_b128 v29, v[108:111] offset:24832
	ds_write_b128 v29, v[112:115] offset:33024
	ds_write_b64 v30, v[90:91] offset:24832
	ds_write_b64 v31, v[116:117] offset:24832
	v_add_u32_e32 v26, s22, v29
	v_add_u32_e32 v27, s22, v30
	v_add_u32_e32 v28, s22, v31
	v_add_u32_e32 v22, 0x8000, v2
	v_add_u32_e32 v23, 0x8000, v3
	v_mov_b32_e32 v6, 0
	v_mov_b32_e32 v7, 0
	v_mov_b32_e32 v8, 0
	v_mov_b32_e32 v9, 0
	v_mov_b32_e32 v10, 0
	v_mov_b32_e32 v11, 0
	v_mov_b32_e32 v12, 0
	v_mov_b32_e32 v13, 0
	v_mov_b32_e32 v14, 0
	v_mov_b32_e32 v15, 0
	v_mov_b32_e32 v16, 0
	v_mov_b32_e32 v17, 0
	v_mov_b32_e32 v18, 0
	v_mov_b32_e32 v19, 0
	v_mov_b32_e32 v20, 0
	v_mov_b32_e32 v21, 0
	s_mov_b32 s16, 0
	s_mov_b32 s2, 0x10001
	s_mov_b32 s3, 0x10001
	s_waitcnt vmcnt(0) lgkmcnt(0)
	s_barrier
	ds_read_b64 v[64:65], v3 offset:20736
	ds_read_b128 v[48:51], v2 offset:8448
	ds_read_b128 v[52:55], v2 offset:8704
	ds_read_b128 v[56:59], v2 offset:8960
	ds_read_b128 v[60:63], v2 offset:9216

.Lgla2_item:
	s_lshr_b32 s0, s18, 5
	s_and_b32 s1, s18, 31
	s_lshr_b32 s2, s0, 2
	s_and_b32 s3, s0, 3
	s_lshl_b32 s4, s1, 4
	v_lshl_add_u32 v46, v5, 2, s4
	s_and_b32 s4, s1, 3
	s_lshl_b32 s4, s4, 5
	v_lshl_add_u32 v3, v5, 3, s4
	s_lshl_b32 s4, s3, 8
	s_add_u32 s4, s4, 1024
	v_lshl_add_u32 v32, v198, 2, s4
	s_add_u32 s4, s4, 4096
	v_lshl_add_u32 v33, v198, 2, s4
	s_lshl_b32 s4, s3, 9
	s_and_b32 s5, s1, 28
	s_lshl_b32 s5, s5, 4
	s_add_u32 s4, s4, s5
	s_add_u32 s4, s4, 2048
	v_min_u32_e32 v42, 31, v198
	v_lshl_add_u32 v34, v42, 2, s4
	v_cmp_lt_u32_e32 vcc, 15, v198
	v_add_u32_e32 v44, 4032, v34
	s_nop 1
	v_cndmask_b32_e32 v34, v34, v44, vcc
	v_readlane_b32 s5, v255, 15
	s_mul_i32 s4, s2, 0x1800000
	s_mul_i32 s1, s5, 0x3000
	s_add_u32 s4, s4, s1
	s_add_u32 s4, s4, 0x3bc0400
	s_add_u32 s10, s8, s4
	s_addc_u32 s11, s9, 0
	s_lshl_b32 s4, s2, 22
	s_lshl_b32 s1, s5, 11
	s_add_u32 s4, s4, s1
	s_lshl_b32 s1, s3, 9
	s_add_u32 s4, s4, s1
	s_add_u32 s4, s4, 0xfd40400
	s_add_u32 s12, s8, s4
	s_addc_u32 s13, s9, 0
	s_lshl_b32 s4, s2, 23
	s_add_u32 s4, s4, s1
	s_add_u32 s4, s4, 333186048
	s_add_u32 s14, s8, s4
	s_addc_u32 s15, s9, 0
	v_mov_b32_e32 v40, 0x3db504f3
	s_movk_i32 s20, 256
	s_movk_i32 s21, 24832
	s_mov_b32 s22, 49408
	v_add_u32_e32 v26, s20, v29
	v_add_u32_e32 v27, s20, v30
	v_add_u32_e32 v28, s20, v31
	global_load_dword v110, v32, s[10:11]
	global_load_dword v111, v32, s[10:11] offset:-1024
	global_load_dword v112, v33, s[10:11]
	global_load_dword v113, v33, s[10:11] offset:-1024
	global_load_dword v114, v34, s[10:11]
	global_load_dword v116, v35, s[12:13]
	global_load_dword v117, v35, s[12:13] offset:4
	s_add_u32 s10, s10, 0x18000
	s_addc_u32 s11, s11, 0
	s_add_u32 s12, s12, 0x4000
	s_addc_u32 s13, s13, 0
	s_waitcnt vmcnt(0)
	v_lshlrev_b32_e32 v144, 16, v110
	v_lshlrev_b32_e32 v145, 16, v111
	v_and_b32_e32 v146, s17, v110
	v_and_b32_e32 v147, s17, v111
	v_lshlrev_b32_e32 v148, 16, v112
	v_lshlrev_b32_e32 v149, 16, v113
	v_and_b32_e32 v150, s17, v112
	v_and_b32_e32 v151, s17, v113
	v_lshlrev_b32_e32 v152, 16, v114
	v_and_b32_e32 v153, s17, v114
	ds_write_b128 v29, v[144:147] offset:256
	ds_write_b128 v29, v[148:151] offset:8448
	ds_write_b64 v30, v[116:117] offset:256
	ds_write_b64 v31, v[152:153] offset:256
	v_add_u32_e32 v26, s21, v29
	v_add_u32_e32 v27, s21, v30
	v_add_u32_e32 v28, s21, v31
	global_load_dword v110, v32, s[10:11]
	global_load_dword v111, v32, s[10:11] offset:-1024
	global_load_dword v112, v33, s[10:11]
	global_load_dword v113, v33, s[10:11] offset:-1024
	global_load_dword v114, v34, s[10:11]
	global_load_dword v116, v35, s[12:13]
	global_load_dword v117, v35, s[12:13] offset:4
	s_add_u32 s10, s10, 0x18000
	s_addc_u32 s11, s11, 0
	s_add_u32 s12, s12, 0x4000
	s_addc_u32 s13, s13, 0
	s_waitcnt vmcnt(0)
	v_lshlrev_b32_e32 v144, 16, v110
	v_lshlrev_b32_e32 v145, 16, v111
	v_and_b32_e32 v146, s17, v110
	v_and_b32_e32 v147, s17, v111
	v_lshlrev_b32_e32 v148, 16, v112
	v_lshlrev_b32_e32 v149, 16, v113
	v_and_b32_e32 v150, s17, v112
	v_and_b32_e32 v151, s17, v113
	v_lshlrev_b32_e32 v152, 16, v114
	v_and_b32_e32 v153, s17, v114
	ds_write_b128 v29, v[144:147] offset:24832
	ds_write_b128 v29, v[148:151] offset:33024
	ds_write_b64 v30, v[116:117] offset:24832
	ds_write_b64 v31, v[152:153] offset:24832
	v_add_u32_e32 v26, s22, v29
	v_add_u32_e32 v27, s22, v30
	v_add_u32_e32 v28, s22, v31
	v_add_u32_e32 v22, 0x8000, v2
	v_add_u32_e32 v23, 0x8000, v3
	v_mov_b32_e32 v6, 0
	v_mov_b32_e32 v7, 0
	v_mov_b32_e32 v8, 0
	v_mov_b32_e32 v9, 0
	v_mov_b32_e32 v10, 0
	v_mov_b32_e32 v11, 0
	v_mov_b32_e32 v12, 0
	v_mov_b32_e32 v13, 0
	v_mov_b32_e32 v14, 0
	v_mov_b32_e32 v15, 0
	v_mov_b32_e32 v16, 0
	v_mov_b32_e32 v17, 0
	v_mov_b32_e32 v18, 0
	v_mov_b32_e32 v19, 0
	v_mov_b32_e32 v20, 0
	v_mov_b32_e32 v21, 0
	s_mov_b32 s16, 0
	s_mov_b32 s2, 0x10001
	s_mov_b32 s3, 0x10001
	s_waitcnt vmcnt(0) lgkmcnt(0)
	s_barrier
	ds_read_b64 v[72:73], v3 offset:20736
	ds_read_b128 v[48:51], v2 offset:256
	ds_read_b128 v[64:67], v2 offset:16640
	ds_read_b128 v[52:55], v2 offset:512
	ds_read_b128 v[56:59], v2 offset:768
	ds_read_b128 v[68:71], v2 offset:16896
	ds_read_b128 v[60:63], v2 offset:1024
